# half of the layer-1 weight conversion items deferred from the prologue into the workgroups with the smaller layer-0 P1 share (second pass of the P0 weight loop after the grid barrier)
# speedup vs baseline: 1.0049x; 1.0049x over previous
.LBB0_14:
	s_or_b64 exec, exec, s[4:5]
	s_load_dwordx2 s[6:7], s[0:1], 0x90
	s_lshr_b32 s42, s38, 6
	v_and_b32_e32 v1, 63, v0
	s_mul_i32 s45, s42, 0x4600
	s_waitcnt lgkmcnt(0)
	s_cmp_lt_i32 s6, 1
	s_cselect_b64 s[4:5], -1, 0
	v_writelane_b32 v252, s6, 2
	s_cmp_gt_i32 s7, 0
	s_nop 0
	v_writelane_b32 v252, s7, 3
	s_cselect_b64 s[6:7], -1, 0
	s_and_b64 s[8:9], s[4:5], s[6:7]
	s_andn2_b64 vcc, exec, s[8:9]
	s_cbranch_vccnz .LBB0_54
	s_mov_b32 s98, 0
	v_writelane_b32 v250, s98, 63
	s_movk_i32 s99, 0x1dff
	s_load_dwordx2 s[10:11], s[0:1], 0x88
	s_lshl_b32 s33, s14, 3
	s_add_i32 s33, s33, s42
	s_cmpk_gt_i32 s33, 0xfff
	s_cbranch_scc1 .LBB0_26
	v_mbcnt_lo_u32_b32 v2, -1, 0
	v_mbcnt_hi_u32_b32 v2, -1, v2
	v_and_b32_e32 v3, 64, v2
	v_add_u32_e32 v3, 64, v3
	v_xor_b32_e32 v4, 1, v2
	v_cmp_lt_i32_e32 vcc, v4, v3
	s_load_dwordx2 s[22:23], s[0:1], 0x0
	s_lshl_b32 s12, s33, 2
	v_cndmask_b32_e32 v4, v2, v4, vcc
	v_lshlrev_b32_e32 v64, 2, v4
	v_xor_b32_e32 v4, 2, v2
	v_cmp_lt_i32_e32 vcc, v4, v3
	s_lshl_b32 s14, s3, 5
	s_ashr_i32 s13, s12, 31
	v_cndmask_b32_e32 v4, v2, v4, vcc
	v_lshlrev_b32_e32 v65, 2, v4
	v_xor_b32_e32 v4, 4, v2
	v_cmp_lt_i32_e32 vcc, v4, v3
	s_lshl_b64 s[16:17], s[12:13], 6
	s_ashr_i32 s15, s14, 31
	v_cndmask_b32_e32 v4, v2, v4, vcc
	v_lshlrev_b32_e32 v66, 2, v4
	v_xor_b32_e32 v4, 8, v2
	v_cmp_lt_i32_e32 vcc, v4, v3
	s_lshl_b64 s[18:19], s[12:13], 10
	v_lshl_or_b32 v50, v1, 2, s16
	v_cndmask_b32_e32 v4, v2, v4, vcc
	v_lshlrev_b32_e32 v67, 2, v4
	v_xor_b32_e32 v4, 16, v2
	v_cmp_lt_i32_e32 vcc, v4, v3
	v_mov_b32_e32 v51, s17
	s_lshl_b64 s[16:17], s[14:15], 6
	v_cndmask_b32_e32 v4, v2, v4, vcc
	v_lshlrev_b32_e32 v68, 2, v4
	v_xor_b32_e32 v4, 32, v2
	v_cmp_lt_i32_e32 vcc, v4, v3
	v_lshl_or_b32 v52, v1, 3, s18
	v_mov_b32_e32 v53, s19
	s_lshl_b64 s[18:19], s[14:15], 10
	s_lshl_b64 s[24:25], s[12:13], 12
	v_cndmask_b32_e32 v2, v2, v4, vcc
	s_waitcnt lgkmcnt(0)
	s_add_u32 s22, s22, s24
	v_lshlrev_b32_e32 v69, 2, v2
	v_lshlrev_b32_e32 v2, 5, v1
	v_mov_b32_e32 v3, 0
	s_addc_u32 s23, s23, s25
	s_mul_hi_i32 s20, s12, 0x2c00
	s_mul_i32 s21, s33, 0xb000
	v_lshl_add_u64 v[2:3], s[22:23], 0, v[2:3]
	s_mov_b64 s[22:23], 0x3810
	s_movk_i32 s24, 0xc7f0
	s_movk_i32 s26, 0xcff0
	s_movk_i32 s28, 0xd7f0
	s_movk_i32 s30, 0xdff0
	s_movk_i32 s34, 0xe7f0
	v_cmp_gt_u32_e64 s[6:7], 16, v1
	v_cmp_eq_u32_e64 s[4:5], 0, v1
	v_lshl_or_b32 v54, v1, 4, s21
	v_mov_b32_e32 v55, s20
	s_mul_i32 s20, s3, 0x58000
	s_mul_hi_i32 s21, s14, 0x2c00
	v_lshl_add_u64 v[56:57], v[2:3], 0, s[22:23]
	s_lshl_b64 s[22:23], s[14:15], 12
	s_mov_b32 s25, -1
	s_mov_b32 s27, -1
	s_mov_b32 s29, -1
	s_movk_i32 s13, 0xe000
	s_mov_b32 s31, -1
	s_mov_b32 s35, -1
	s_movk_i32 s15, 0xf000
	s_mov_b32 s43, 0x2202000
	s_mov_b32 s44, 0xd200000
	s_mov_b32 s46, 0x2205000
	s_mov_b32 s47, 0x2207000
	s_mov_b32 s48, 0x220a000
	s_branch .LBB0_18

.LBB0_26:
	s_cmp_gt_i32 s33, s99
	s_cbranch_scc1 .LBB0_47
	v_lshrrev_b32_e32 v54, 5, v1
	v_and_b32_e32 v2, 31, v0
	s_add_i32 s12, s45, 0
	s_lshl_b32 s34, s3, 3
	v_lshlrev_b32_e32 v4, 2, v2
	v_mul_u32_u24_e32 v5, 0x84, v54
	s_waitcnt lgkmcnt(0)
	s_add_u32 s35, s10, 0x500000
	v_add3_u32 v55, s12, v4, v5
	v_lshlrev_b32_e32 v5, 3, v0
	s_addc_u32 s36, s11, 0
	v_lshrrev_b32_e32 v4, 3, v1
	v_and_b32_e32 v10, 56, v5
	s_add_u32 s37, s10, 0x1700000
	v_mul_u32_u24_e32 v5, 0x84, v10
	v_lshlrev_b32_e32 v6, 2, v4
	v_lshlrev_b32_e32 v12, 10, v4
	v_mul_u32_u24_e32 v8, 0x600, v4
	v_lshlrev_b32_e32 v4, 5, v0
	s_addc_u32 s43, s11, 0
	v_add3_u32 v56, s12, v5, v6
	v_lshrrev_b32_e32 v5, 1, v1
	v_and_b32_e32 v4, 32, v4
	s_load_dwordx4 s[4:7], s[0:1], 0x8
	s_add_u32 s44, s10, 0x1d00000
	v_mul_u32_u24_e32 v6, 0x84, v4
	v_lshlrev_b32_e32 v7, 2, v5
	s_addc_u32 s46, s11, 0
	v_add3_u32 v57, s12, v6, v7
	s_load_dwordx2 s[12:13], s[0:1], 0x70
	s_add_u32 s50, s10, 0xe200000
	s_addc_u32 s51, s11, 0
	v_mov_b32_e32 v3, 0
	v_or_b32_e32 v14, 0x2000, v12
	v_or_b32_e32 v16, 0x4000, v12
	v_or_b32_e32 v18, 0x6000, v12
	s_waitcnt lgkmcnt(0)
	s_cmp_lg_u64 s[4:5], 0
	s_mov_b32 s18, 0xffb80000
	s_movk_i32 s47, 0x2000
	s_movk_i32 s48, 0x4000
	s_movk_i32 s49, 0x6000
	v_lshlrev_b32_e32 v6, 10, v5
	v_mov_b32_e32 v7, v3
	v_mov_b32_e32 v5, v3
	s_cselect_b64 s[14:15], -1, 0
	s_lshl_b32 s52, s33, 5
	s_lshl_b32 s53, s3, 8
	s_lshl_b32 s54, s33, 1
	s_lshl_b32 s55, s3, 4
	s_mov_b32 s56, 0x8000
	s_mov_b32 s57, 0xa000
	s_mov_b32 s58, 0xc000
	s_mov_b32 s59, 0xe000
	s_mov_b32 s60, 0x10000
	s_mov_b32 s61, 0x12000
	s_mov_b32 s62, 0x14000
	s_mov_b32 s63, 0x16000
	s_mov_b32 s64, 0x18000
	s_mov_b32 s65, 0x1a000
	s_mov_b32 s66, 0x1c000
	s_mov_b32 s67, 0x1e000
	s_mov_b32 s68, 0x20000
	s_mov_b32 s69, 0x22000
	s_mov_b32 s70, 0x24000
	s_mov_b32 s71, 0x26000
	s_mov_b32 s72, 0x28000
	s_mov_b32 s73, 0x2a000
	s_mov_b32 s74, 0x2c000
	s_mov_b32 s75, 0x2e000
	s_mov_b32 s76, 0x30000
	s_mov_b32 s77, 0x32000
	s_mov_b32 s78, 0x34000
	s_mov_b32 s79, 0x36000
	s_mov_b32 s80, 0x38000
	s_mov_b32 s81, 0x3a000
	s_mov_b32 s82, 0x3c000
	s_mov_b32 s83, 0x3e000
	v_lshlrev_b32_e32 v8, 1, v8
	v_lshlrev_b32_e32 v2, 2, v2
	v_add_u32_e32 v58, 0x400, v55
	v_add_u32_e32 v59, 0x800, v55
	v_add_u32_e32 v60, 0xc00, v55
	v_add_u32_e32 v61, 0x1000, v55
	v_add_u32_e32 v62, 0x1400, v55
	v_add_u32_e32 v63, 0x1800, v55
	v_add_u32_e32 v64, 0x1c00, v55
	v_lshlrev_b32_e32 v10, 1, v10
	v_lshlrev_b32_e32 v12, 1, v12
	v_lshlrev_b32_e32 v14, 1, v14
	v_lshlrev_b32_e32 v16, 1, v16
	v_lshlrev_b32_e32 v18, 1, v18
	s_mov_b32 s84, 0x168000
	s_mov_b32 s85, 0x177000
	s_mov_b32 s86, 0x186000
	s_mov_b32 s87, 0x195000
	s_mov_b32 s88, 0x1a4000
	s_mov_b32 s89, 0x1b3000
	s_mov_b32 s90, 0x1c2000
	s_mov_b32 s91, 0x1d1000
	s_movk_i32 s92, 0x1000
	s_mov_b32 s93, s33
	s_mov_b32 s17, 0
	s_mov_b32 s19, -1
	s_branch .LBB0_30

.LBB0_29:
	s_add_i32 s93, s93, s34
	s_add_i32 s52, s52, s53
	s_add_i32 s54, s54, s55
	s_cmp_gt_i32 s93, s99
	s_cbranch_scc1 .LBB0_47

.LBB0_47:
	v_readlane_b32 s98, v250, 63
	s_cmp_lg_u32 s98, 0
	s_cbranch_scc1 .Lp0b_ret
	v_lshl_or_b32 v2, s33, 6, v1
	s_mov_b32 s4, 0x20000
	v_cmp_gt_i32_e32 vcc, s4, v2
	v_ashrrev_i32_e32 v3, 31, v2
	s_and_saveexec_b64 s[6:7], vcc
	s_cbranch_execz .LBB0_50
	s_load_dwordx2 s[12:13], s[0:1], 0x28
	s_lshl_b32 s14, s3, 9
	s_waitcnt lgkmcnt(0)
	v_lshl_add_u64 v[4:5], v[2:3], 2, s[10:11]
	s_mov_b64 s[4:5], 0x2100000
	s_ashr_i32 s15, s14, 31
	v_lshl_add_u64 v[4:5], v[4:5], 0, s[4:5]
	s_lshl_b64 s[16:17], s[14:15], 2
	v_lshlrev_b32_e32 v6, 1, v2
	s_lshl_b32 s15, s3, 10
	s_mov_b64 s[18:19], 0
	s_mov_b32 s20, 0x1ffff
	v_mov_b32_e32 v8, v2

.LBB0_90:
	s_cmpk_lt_i32 s2, 0x80
	s_cbranch_scc1 .Lp0b_skip
	v_writelane_b32 v248, s0, 0
	v_writelane_b32 v248, s1, 1
	v_writelane_b32 v248, s2, 2
	v_writelane_b32 v248, s3, 3
	v_writelane_b32 v248, s4, 4
	v_writelane_b32 v248, s5, 5
	v_writelane_b32 v248, s6, 6
	v_writelane_b32 v248, s7, 7
	v_writelane_b32 v248, s8, 8
	v_writelane_b32 v248, s9, 9
	v_writelane_b32 v248, s10, 10
	v_writelane_b32 v248, s11, 11
	v_writelane_b32 v248, s12, 12
	v_writelane_b32 v248, s13, 13
	v_writelane_b32 v248, s14, 14
	v_writelane_b32 v248, s15, 15
	v_writelane_b32 v248, s16, 16
	v_writelane_b32 v248, s17, 17
	v_writelane_b32 v248, s18, 18
	v_writelane_b32 v248, s19, 19
	v_writelane_b32 v248, s20, 20
	v_writelane_b32 v248, s21, 21
	v_writelane_b32 v248, s22, 22
	v_writelane_b32 v248, s23, 23
	v_writelane_b32 v248, s24, 24
	v_writelane_b32 v248, s25, 25
	v_writelane_b32 v248, s26, 26
	v_writelane_b32 v248, s27, 27
	v_writelane_b32 v248, s28, 28
	v_writelane_b32 v248, s29, 29
	v_writelane_b32 v248, s30, 30
	v_writelane_b32 v248, s31, 31
	v_writelane_b32 v248, s32, 32
	v_writelane_b32 v248, s33, 33
	v_writelane_b32 v248, s34, 34
	v_writelane_b32 v248, s35, 35
	v_writelane_b32 v248, s36, 36
	v_writelane_b32 v248, s37, 37
	v_writelane_b32 v248, s38, 38
	v_writelane_b32 v248, s39, 39
	v_writelane_b32 v248, s40, 40
	v_writelane_b32 v248, s41, 41
	v_writelane_b32 v248, s42, 42
	v_writelane_b32 v248, s43, 43
	v_writelane_b32 v248, s44, 44
	v_writelane_b32 v248, s45, 45
	v_writelane_b32 v248, s46, 46
	v_writelane_b32 v248, s47, 47
	v_writelane_b32 v248, s48, 48
	v_writelane_b32 v248, s49, 49
	v_writelane_b32 v248, s50, 50
	v_writelane_b32 v248, s51, 51
	v_writelane_b32 v248, s52, 52
	v_writelane_b32 v248, s53, 53
	v_writelane_b32 v248, s54, 54
	v_writelane_b32 v248, s55, 55
	v_writelane_b32 v248, s56, 56
	v_writelane_b32 v248, s57, 57
	v_writelane_b32 v248, s58, 58
	v_writelane_b32 v248, s59, 59
	v_writelane_b32 v248, s60, 60
	v_writelane_b32 v248, s61, 61
	v_writelane_b32 v248, s62, 62
	v_writelane_b32 v248, s63, 63
	v_writelane_b32 v249, s64, 0
	v_writelane_b32 v249, s65, 1
	v_writelane_b32 v249, s66, 2
	v_writelane_b32 v249, s67, 3
	v_writelane_b32 v249, s68, 4
	v_writelane_b32 v249, s69, 5
	v_writelane_b32 v249, s70, 6
	v_writelane_b32 v249, s71, 7
	v_writelane_b32 v249, s72, 8
	v_writelane_b32 v249, s73, 9
	v_writelane_b32 v249, s74, 10
	v_writelane_b32 v249, s75, 11
	v_writelane_b32 v249, s76, 12
	v_writelane_b32 v249, s77, 13
	v_writelane_b32 v249, s78, 14
	v_writelane_b32 v249, s79, 15
	v_writelane_b32 v249, s80, 16
	v_writelane_b32 v249, s81, 17
	v_writelane_b32 v249, s82, 18
	v_writelane_b32 v249, s83, 19
	v_writelane_b32 v249, s84, 20
	v_writelane_b32 v249, s85, 21
	v_writelane_b32 v249, s86, 22
	v_writelane_b32 v249, s87, 23
	v_writelane_b32 v249, s88, 24
	v_writelane_b32 v249, s89, 25
	v_writelane_b32 v249, s90, 26
	v_writelane_b32 v249, s91, 27
	v_writelane_b32 v249, s92, 28
	v_writelane_b32 v249, s93, 29
	v_writelane_b32 v249, s94, 30
	v_writelane_b32 v249, s95, 31
	v_writelane_b32 v249, s96, 32
	v_writelane_b32 v249, s97, 33
	s_mov_b32 s98, 1
	v_writelane_b32 v250, s98, 63
	s_movk_i32 s99, 0x27ff
	s_and_b32 s33, s2, 7
	s_lshl_b32 s33, s33, 4
	s_lshr_b32 s4, s2, 3
	s_add_i32 s33, s33, s4
	s_sub_i32 s33, s33, 16
	s_lshl_b32 s33, s33, 3
	s_add_i32 s33, s33, s42
	s_addk_i32 s33, 0x1e00
	s_movk_i32 s3, 0x80
	s_load_dwordx2 s[10:11], s[0:1], 0x88
	s_branch .LBB0_26
.Lp0b_ret:
	s_waitcnt lgkmcnt(0)
	s_barrier
	v_readlane_b32 s0, v248, 0
	v_readlane_b32 s1, v248, 1
	v_readlane_b32 s2, v248, 2
	v_readlane_b32 s3, v248, 3
	v_readlane_b32 s4, v248, 4
	v_readlane_b32 s5, v248, 5
	v_readlane_b32 s6, v248, 6
	v_readlane_b32 s7, v248, 7
	v_readlane_b32 s8, v248, 8
	v_readlane_b32 s9, v248, 9
	v_readlane_b32 s10, v248, 10
	v_readlane_b32 s11, v248, 11
	v_readlane_b32 s12, v248, 12
	v_readlane_b32 s13, v248, 13
	v_readlane_b32 s14, v248, 14
	v_readlane_b32 s15, v248, 15
	v_readlane_b32 s16, v248, 16
	v_readlane_b32 s17, v248, 17
	v_readlane_b32 s18, v248, 18
	v_readlane_b32 s19, v248, 19
	v_readlane_b32 s20, v248, 20
	v_readlane_b32 s21, v248, 21
	v_readlane_b32 s22, v248, 22
	v_readlane_b32 s23, v248, 23
	v_readlane_b32 s24, v248, 24
	v_readlane_b32 s25, v248, 25
	v_readlane_b32 s26, v248, 26
	v_readlane_b32 s27, v248, 27
	v_readlane_b32 s28, v248, 28
	v_readlane_b32 s29, v248, 29
	v_readlane_b32 s30, v248, 30
	v_readlane_b32 s31, v248, 31
	v_readlane_b32 s32, v248, 32
	v_readlane_b32 s33, v248, 33
	v_readlane_b32 s34, v248, 34
	v_readlane_b32 s35, v248, 35
	v_readlane_b32 s36, v248, 36
	v_readlane_b32 s37, v248, 37
	v_readlane_b32 s38, v248, 38
	v_readlane_b32 s39, v248, 39
	v_readlane_b32 s40, v248, 40
	v_readlane_b32 s41, v248, 41
	v_readlane_b32 s42, v248, 42
	v_readlane_b32 s43, v248, 43
	v_readlane_b32 s44, v248, 44
	v_readlane_b32 s45, v248, 45
	v_readlane_b32 s46, v248, 46
	v_readlane_b32 s47, v248, 47
	v_readlane_b32 s48, v248, 48
	v_readlane_b32 s49, v248, 49
	v_readlane_b32 s50, v248, 50
	v_readlane_b32 s51, v248, 51
	v_readlane_b32 s52, v248, 52
	v_readlane_b32 s53, v248, 53
	v_readlane_b32 s54, v248, 54
	v_readlane_b32 s55, v248, 55
	v_readlane_b32 s56, v248, 56
	v_readlane_b32 s57, v248, 57
	v_readlane_b32 s58, v248, 58
	v_readlane_b32 s59, v248, 59
	v_readlane_b32 s60, v248, 60
	v_readlane_b32 s61, v248, 61
	v_readlane_b32 s62, v248, 62
	v_readlane_b32 s63, v248, 63
	v_readlane_b32 s64, v249, 0
	v_readlane_b32 s65, v249, 1
	v_readlane_b32 s66, v249, 2
	v_readlane_b32 s67, v249, 3
	v_readlane_b32 s68, v249, 4
	v_readlane_b32 s69, v249, 5
	v_readlane_b32 s70, v249, 6
	v_readlane_b32 s71, v249, 7
	v_readlane_b32 s72, v249, 8
	v_readlane_b32 s73, v249, 9
	v_readlane_b32 s74, v249, 10
	v_readlane_b32 s75, v249, 11
	v_readlane_b32 s76, v249, 12
	v_readlane_b32 s77, v249, 13
	v_readlane_b32 s78, v249, 14
	v_readlane_b32 s79, v249, 15
	v_readlane_b32 s80, v249, 16
	v_readlane_b32 s81, v249, 17
	v_readlane_b32 s82, v249, 18
	v_readlane_b32 s83, v249, 19
	v_readlane_b32 s84, v249, 20
	v_readlane_b32 s85, v249, 21
	v_readlane_b32 s86, v249, 22
	v_readlane_b32 s87, v249, 23
	v_readlane_b32 s88, v249, 24
	v_readlane_b32 s89, v249, 25
	v_readlane_b32 s90, v249, 26
	v_readlane_b32 s91, v249, 27
	v_readlane_b32 s92, v249, 28
	v_readlane_b32 s93, v249, 29
	v_readlane_b32 s94, v249, 30
	v_readlane_b32 s95, v249, 31
	v_readlane_b32 s96, v249, 32
	v_readlane_b32 s97, v249, 33
	s_nop 4
